# v23 + GLA/HGRN2 intra-chunk stages straightened and LDS-read pipelined
# baseline (speedup 1.0000x reference)
.LBB0_719:
	ds_read_b128 v[70:73], v233
	s_nop 0
	s_add_u32 s22, s77, s71
	s_addc_u32 s23, 0, s72
	v_cmp_gt_i32_e32 vcc, s78, v161
	s_waitcnt lgkmcnt(1)
	s_waitcnt lgkmcnt(0)
	v_mfma_f32_16x16x32_bf16 v[150:153], v[134:137], v[70:73], v[150:153]
	ds_read_b128 v[70:73], v233 offset:2304
	ds_read_b128 v[74:77], v233 offset:2368
	ds_read_b128 v[78:81], v233 offset:4608
	ds_read_b128 v[82:85], v233 offset:4672
	ds_read_b128 v[86:89], v233 offset:6912
	ds_read_b128 v[234:237], v233 offset:64
	s_waitcnt lgkmcnt(0)
	v_mfma_f32_16x16x32_bf16 v[150:153], v[130:133], v[234:237], v[150:153]
	ds_read_b128 v[90:93], v233 offset:6976
	s_and_saveexec_b64 s[24:25], vcc
	s_nop 0
	v_mov_b32_e32 v235, s23
	v_or_b32_e32 v234, s22, v161
	v_lshlrev_b64 v[234:235], 13, v[234:235]
	s_nop 2
	v_cvt_pk_bf16_f32 v36, v150, v151
	v_cvt_pk_bf16_f32 v37, v152, v153
	v_lshl_add_u64 v[234:235], v[176:177], 0, v[234:235]
	global_store_dwordx2 v[234:235], v[36:37], off
	s_or_b64 exec, exec, s[24:25]
	v_and_b32_e32 v35, 64, v229
	v_xor_b32_e32 v1, 16, v229
	v_add_u32_e32 v36, 64, v35
	v_cmp_lt_i32_e32 vcc, v1, v36
	s_nop 0
	v_mul_f32_e32 v37, v153, v153
	v_fmac_f32_e32 v37, v152, v152
	v_cndmask_b32_e32 v1, v229, v1, vcc
	v_lshlrev_b32_e32 v35, 2, v1
	v_mul_f32_e32 v1, v151, v151
	v_fmac_f32_e32 v1, v150, v150
	v_add_f32_e32 v1, v1, v37
	ds_bpermute_b32 v37, v35, v1
	v_xor_b32_e32 v150, 32, v229
	v_cmp_lt_i32_e32 vcc, v150, v36
	s_waitcnt lgkmcnt(0)
	v_add_f32_e32 v37, v1, v37
	v_cndmask_b32_e32 v36, v229, v150, vcc
	v_lshlrev_b32_e32 v36, 2, v36
	ds_bpermute_b32 v150, v36, v37
	s_and_saveexec_b64 s[24:25], s[38:39]
	s_nop 0
	s_waitcnt lgkmcnt(0)
	v_add_f32_e32 v1, v37, v150
	ds_write_b32 v214, v1
	s_or_b64 exec, exec, s[24:25]
	s_nop 0
	s_nop 0
	s_min_i32 s26, s78, 64
	v_cmp_gt_i32_e32 vcc, s26, v162
	s_nop 0
	v_mfma_f32_16x16x32_bf16 v[146:149], v[134:137], v[70:73], v[146:149]
	s_nop 0
	s_nop 0
	v_mfma_f32_16x16x32_bf16 v[146:149], v[130:133], v[74:77], v[146:149]
	s_and_saveexec_b64 s[24:25], vcc
	s_nop 0
	v_mov_b32_e32 v153, s23
	v_or_b32_e32 v152, s22, v162
	v_lshlrev_b64 v[152:153], 13, v[152:153]
	s_nop 2
	v_cvt_pk_bf16_f32 v150, v146, v147
	v_cvt_pk_bf16_f32 v151, v148, v149
	v_lshl_add_u64 v[152:153], v[176:177], 0, v[152:153]
	global_store_dwordx2 v[152:153], v[150:151], off
	s_or_b64 exec, exec, s[24:25]
	s_nop 4
	v_mul_f32_e32 v1, v147, v147
	v_mul_f32_e32 v37, v149, v149
	v_fmac_f32_e32 v1, v146, v146
	v_fmac_f32_e32 v37, v148, v148
	v_add_f32_e32 v1, v1, v37
	ds_bpermute_b32 v37, v35, v1
	s_waitcnt lgkmcnt(0)
	v_add_f32_e32 v37, v1, v37
	ds_bpermute_b32 v146, v36, v37
	s_and_saveexec_b64 s[24:25], s[38:39]
	s_nop 0
	s_waitcnt lgkmcnt(0)
	v_add_f32_e32 v1, v37, v146
	ds_write_b32 v215, v1
	s_or_b64 exec, exec, s[24:25]
	s_nop 0
	s_nop 0
	v_cmp_gt_i32_e32 vcc, s26, v172
	s_nop 0
	v_mfma_f32_16x16x32_bf16 v[142:145], v[134:137], v[78:81], v[142:145]
	s_nop 0
	s_nop 0
	v_mfma_f32_16x16x32_bf16 v[142:145], v[130:133], v[82:85], v[142:145]
	s_and_saveexec_b64 s[24:25], vcc
	s_nop 0
	v_lshl_add_u64 v[148:149], s[22:23], 0, v[172:173]
	v_lshlrev_b64 v[148:149], 13, v[148:149]
	s_nop 3
	v_cvt_pk_bf16_f32 v146, v142, v143
	v_cvt_pk_bf16_f32 v147, v144, v145
	v_lshl_add_u64 v[148:149], v[176:177], 0, v[148:149]
	global_store_dwordx2 v[148:149], v[146:147], off
	s_or_b64 exec, exec, s[24:25]
	s_nop 4
	v_mul_f32_e32 v1, v143, v143
	v_mul_f32_e32 v37, v145, v145
	v_fmac_f32_e32 v1, v142, v142
	v_fmac_f32_e32 v37, v144, v144
	v_add_f32_e32 v1, v1, v37
	ds_bpermute_b32 v37, v35, v1
	s_waitcnt lgkmcnt(0)
	v_add_f32_e32 v37, v1, v37
	ds_bpermute_b32 v142, v36, v37
	s_and_saveexec_b64 s[24:25], s[38:39]
	s_nop 0
	s_waitcnt lgkmcnt(0)
	v_add_f32_e32 v1, v37, v142
	ds_write_b32 v216, v1
	s_or_b64 exec, exec, s[24:25]
	s_nop 0
	s_nop 0
	v_cmp_gt_i32_e32 vcc, s26, v174
	s_nop 0
	v_mfma_f32_16x16x32_bf16 v[138:141], v[134:137], v[86:89], v[138:141]
	s_nop 0
	s_nop 0
	v_mfma_f32_16x16x32_bf16 v[138:141], v[130:133], v[90:93], v[138:141]
	s_and_saveexec_b64 s[24:25], vcc
	s_nop 0
	v_lshl_add_u64 v[144:145], s[22:23], 0, v[174:175]
	v_lshlrev_b64 v[144:145], 13, v[144:145]
	s_nop 3
	v_cvt_pk_bf16_f32 v142, v138, v139
	v_cvt_pk_bf16_f32 v143, v140, v141
	v_lshl_add_u64 v[144:145], v[176:177], 0, v[144:145]
	global_store_dwordx2 v[144:145], v[142:143], off
	s_or_b64 exec, exec, s[24:25]
	s_nop 4
	v_mul_f32_e32 v1, v139, v139
	v_mul_f32_e32 v37, v141, v141
	v_fmac_f32_e32 v1, v138, v138
	v_fmac_f32_e32 v37, v140, v140
	v_add_f32_e32 v1, v1, v37
	ds_bpermute_b32 v35, v35, v1
	s_waitcnt lgkmcnt(0)
	v_add_f32_e32 v35, v1, v35
	ds_bpermute_b32 v36, v36, v35
	s_and_saveexec_b64 s[24:25], s[38:39]
	s_cbranch_execz .LBB0_735
	s_waitcnt lgkmcnt(0)
	v_add_f32_e32 v1, v35, v36
	ds_write_b32 v217, v1

.LBB0_839:
	s_nop 7
	v_cndmask_b32_e64 v1, v66, 0, s[54:55]
	v_cndmask_b32_e64 v35, v67, 0, s[56:57]
	v_cndmask_b32_e64 v37, v68, 0, s[58:59]
	v_cndmask_b32_e64 v67, v69, 0, s[60:61]
	v_cvt_pk_bf16_f32 v66, v1, v35
	v_cvt_pk_bf16_f32 v67, v37, v67
	ds_write_b64 v161, v[66:67]
	ds_read_b128 v[184:187], v132
	ds_read_b128 v[188:191], v135
	s_nop 0
	s_nop 0
	v_add_u32_e32 v1, 0x1000, v162
	ds_read_b64 v[192:193], v1 offset:256
	ds_read_b64 v[194:195], v1 offset:288
	ds_read_b64 v[196:197], v162
	ds_read_b64 v[198:199], v162 offset:32
	v_add_u32_e32 v35, 0x2000, v162
	ds_read_b64 v[200:201], v35 offset:512
	ds_read_b64 v[202:203], v35 offset:544
	v_add_u32_e32 v37, 0x3000, v162
	ds_read_b64 v[204:205], v37 offset:768
	ds_read_b64 v[206:207], v37 offset:800
	s_waitcnt lgkmcnt(11)
	s_waitcnt lgkmcnt(9)
	v_pk_mul_f32 v[68:69], v[4:5], v[186:187]
	ds_read_b128 v[208:211], v136
	v_pk_mul_f32 v[66:67], v[2:3], v[184:185]
	s_waitcnt lgkmcnt(9)
	v_pk_mul_f32 v[72:73], v[12:13], v[190:191]
	ds_read_b128 v[184:187], v137
	v_cvt_pk_bf16_f32 v66, v66, v67
	v_cvt_pk_bf16_f32 v67, v68, v69
	v_pk_mul_f32 v[68:69], v[10:11], v[188:189]
	s_nop 0
	v_cvt_pk_bf16_f32 v68, v68, v69
	v_cvt_pk_bf16_f32 v69, v72, v73
	s_nop 0
	s_nop 0
	s_nop 0
	s_waitcnt lgkmcnt(6)
	v_mfma_f32_16x16x32_bf16 v[70:73], v[66:69], v[196:199], 0
	s_sub_i32 s5, s8, 64
	s_add_u32 s18, s5, s72
	s_addc_u32 s19, 0, s74
	v_mfma_f32_16x16x32_bf16 v[74:77], v[66:69], v[192:195], 0
	ds_read_b64 v[188:189], v162 offset:64
	ds_read_b64 v[190:191], v162 offset:96
	ds_read_b64 v[192:193], v1 offset:320
	ds_read_b64 v[194:195], v1 offset:352
	v_mov_b32_e32 v36, 0
	v_cmp_gt_i32_e64 s[68:69], s9, v95
	v_or_b32_e32 v116, s18, v95
	s_waitcnt lgkmcnt(8)
	v_mfma_f32_16x16x32_bf16 v[78:81], v[66:69], v[200:203], 0
	ds_read_b64 v[196:197], v35 offset:576
	ds_read_b64 v[198:199], v35 offset:608
	s_waitcnt lgkmcnt(8)
	v_mfma_f32_16x16x32_bf16 v[66:69], v[66:69], v[204:207], 0
	ds_read_b64 v[200:201], v37 offset:832
	ds_read_b64 v[202:203], v37 offset:864
	s_nop 0
	s_nop 0
	s_waitcnt lgkmcnt(9)
	v_pk_mul_f32 v[106:107], v[8:9], v[210:211]
	ds_read_b128 v[204:207], v138
	v_pk_mul_f32 v[104:105], v[6:7], v[208:209]
	s_waitcnt lgkmcnt(9)
	v_pk_mul_f32 v[110:111], v[16:17], v[186:187]
	ds_read_b128 v[208:211], v139
	v_cvt_pk_bf16_f32 v104, v104, v105
	v_cvt_pk_bf16_f32 v105, v106, v107
	v_pk_mul_f32 v[106:107], v[14:15], v[184:185]
	s_nop 0
	v_cvt_pk_bf16_f32 v106, v106, v107
	v_cvt_pk_bf16_f32 v107, v110, v111
	s_nop 0
	s_waitcnt lgkmcnt(8)
	v_mfma_f32_16x16x32_bf16 v[70:73], v[104:107], v[188:191], v[70:73]
	ds_read_b64 v[184:185], v162 offset:128
	ds_read_b64 v[186:187], v162 offset:160
	s_nop 0
	s_waitcnt lgkmcnt(8)
	v_mfma_f32_16x16x32_bf16 v[74:77], v[104:107], v[192:195], v[74:77]
	ds_read_b64 v[188:189], v1 offset:384
	ds_read_b64 v[190:191], v1 offset:416
	s_nop 0
	s_waitcnt lgkmcnt(8)
	v_mfma_f32_16x16x32_bf16 v[78:81], v[104:107], v[196:199], v[78:81]
	ds_read_b64 v[192:193], v35 offset:640
	ds_read_b64 v[194:195], v35 offset:672
	s_nop 0
	s_waitcnt lgkmcnt(8)
	v_mfma_f32_16x16x32_bf16 v[66:69], v[104:107], v[200:203], v[66:69]
	ds_read_b64 v[196:197], v37 offset:896
	ds_read_b64 v[198:199], v37 offset:928
	s_nop 0
	s_nop 0
	s_waitcnt lgkmcnt(9)
	v_pk_mul_f32 v[106:107], v[20:21], v[206:207]
	ds_read_b128 v[200:203], v140
	v_pk_mul_f32 v[104:105], v[18:19], v[204:205]
	s_waitcnt lgkmcnt(9)
	v_pk_mul_f32 v[110:111], v[24:25], v[210:211]
	ds_read_b128 v[204:207], v141
	v_cvt_pk_bf16_f32 v104, v104, v105
	v_cvt_pk_bf16_f32 v105, v106, v107
	v_pk_mul_f32 v[106:107], v[22:23], v[208:209]
	s_nop 0
	v_cvt_pk_bf16_f32 v106, v106, v107
	v_cvt_pk_bf16_f32 v107, v110, v111
	s_nop 0
	s_waitcnt lgkmcnt(8)
	v_mfma_f32_16x16x32_bf16 v[70:73], v[104:107], v[184:187], v[70:73]
	ds_read_b64 v[184:185], v162 offset:192
	ds_read_b64 v[186:187], v162 offset:224
	s_nop 0
	s_waitcnt lgkmcnt(8)
	v_mfma_f32_16x16x32_bf16 v[74:77], v[104:107], v[188:191], v[74:77]
	ds_read_b64 v[188:189], v1 offset:448
	ds_read_b64 v[190:191], v1 offset:480
	s_nop 0
	s_waitcnt lgkmcnt(8)
	v_mfma_f32_16x16x32_bf16 v[78:81], v[104:107], v[192:195], v[78:81]
	ds_read_b64 v[192:193], v35 offset:704
	ds_read_b64 v[194:195], v35 offset:736
	s_nop 0
	s_waitcnt lgkmcnt(8)
	v_mfma_f32_16x16x32_bf16 v[66:69], v[104:107], v[196:199], v[66:69]
	s_nop 0
	s_nop 0
	s_waitcnt lgkmcnt(7)
	v_pk_mul_f32 v[106:107], v[28:29], v[202:203]
	v_pk_mul_f32 v[104:105], v[26:27], v[200:201]
	s_waitcnt lgkmcnt(6)
	v_pk_mul_f32 v[110:111], v[32:33], v[206:207]
	v_cvt_pk_bf16_f32 v104, v104, v105
	v_cvt_pk_bf16_f32 v105, v106, v107
	v_pk_mul_f32 v[106:107], v[30:31], v[204:205]
	s_nop 0
	v_cvt_pk_bf16_f32 v106, v106, v107
	v_cvt_pk_bf16_f32 v107, v110, v111
	s_nop 0
	s_waitcnt lgkmcnt(4)
	v_mfma_f32_16x16x32_bf16 v[108:111], v[104:107], v[184:187], v[70:73]
	s_nop 2
	s_nop 0
	s_waitcnt lgkmcnt(2)
	v_mfma_f32_16x16x32_bf16 v[74:77], v[104:107], v[188:191], v[74:77]
	s_nop 0
	s_waitcnt lgkmcnt(0)
	v_mfma_f32_16x16x32_bf16 v[70:73], v[104:107], v[192:195], v[78:81]
	s_nop 2
	ds_read_b64 v[78:79], v37 offset:960
	ds_read_b64 v[80:81], v37 offset:992
	s_waitcnt lgkmcnt(0)
	v_mfma_f32_16x16x32_bf16 v[66:69], v[104:107], v[78:81], v[66:69]
	s_barrier
	ds_read_b128 v[184:187], v174
	ds_read_b128 v[188:191], v174 offset:64
	ds_read_b128 v[192:195], v174 offset:2304
	ds_read_b128 v[196:199], v174 offset:2368
	ds_read_b128 v[200:203], v174 offset:4608
	ds_read_b128 v[204:207], v174 offset:4672
	s_nop 0
	s_nop 0
	s_waitcnt lgkmcnt(6)
	s_waitcnt lgkmcnt(5)
	v_mfma_f32_16x16x32_bf16 v[78:81], v[62:65], v[184:187], v[108:111]
	ds_read_b128 v[184:187], v174 offset:6912
	v_mov_b32_e32 v37, 0
	s_waitcnt lgkmcnt(5)
	v_mfma_f32_16x16x32_bf16 v[78:81], v[58:61], v[188:191], v[78:81]
	ds_read_b128 v[188:191], v174 offset:6976
	s_and_saveexec_b64 s[20:21], s[68:69]
	s_nop 0
	v_mov_b32_e32 v117, s19
	v_lshlrev_b64 v[36:37], 12, v[116:117]
	v_lshl_add_u64 v[36:37], v[102:103], 0, v[36:37]
	global_load_dwordx2 v[36:37], v[36:37], off
	s_or_b64 exec, exec, s[20:21]
	v_and_b32_e32 v35, 64, v229
	v_xor_b32_e32 v1, 16, v229
	v_add_u32_e32 v90, 64, v35
	v_cmp_lt_i32_e32 vcc, v1, v90
	s_nop 0
	v_mul_f32_e32 v104, v81, v81
	v_fmac_f32_e32 v104, v80, v80
	v_cndmask_b32_e32 v1, v229, v1, vcc
	v_lshlrev_b32_e32 v35, 2, v1
	v_mul_f32_e32 v1, v79, v79
	v_fmac_f32_e32 v1, v78, v78
	v_add_f32_e32 v1, v1, v104
	ds_bpermute_b32 v104, v35, v1
	v_xor_b32_e32 v105, 32, v229
	v_cmp_lt_i32_e32 vcc, v105, v90
	s_waitcnt lgkmcnt(0)
	v_add_f32_e32 v104, v1, v104
	v_cndmask_b32_e32 v90, v229, v105, vcc
	v_lshlrev_b32_e32 v90, 2, v90
	ds_bpermute_b32 v105, v90, v104
	s_and_saveexec_b64 s[20:21], s[36:37]
	s_nop 0
	s_waitcnt lgkmcnt(0)
	v_add_f32_e32 v1, v104, v105
	v_add_u32_e32 v104, s95, v142
	ds_write_b32 v104, v1
	s_or_b64 exec, exec, s[20:21]
	s_nop 0
	s_nop 0
	s_min_i32 s5, s9, 64
	v_cmp_gt_i32_e64 s[66:67], s5, v94
	v_mov_b32_e32 v114, 0
	v_or_b32_e32 v112, s18, v94
	s_nop 0
	v_mfma_f32_16x16x32_bf16 v[74:77], v[62:65], v[192:195], v[74:77]
	s_nop 0
	v_mov_b32_e32 v115, 0
	s_nop 0
	v_mfma_f32_16x16x32_bf16 v[74:77], v[58:61], v[196:199], v[74:77]
	s_and_saveexec_b64 s[20:21], s[66:67]
	s_nop 0
	v_mov_b32_e32 v113, s19
	v_lshlrev_b64 v[104:105], 12, v[112:113]
	v_lshl_add_u64 v[104:105], v[102:103], 0, v[104:105]
	global_load_dwordx2 v[114:115], v[104:105], off
	s_or_b64 exec, exec, s[20:21]
	s_nop 4
	v_mul_f32_e32 v1, v75, v75
	v_mul_f32_e32 v104, v77, v77
	v_fmac_f32_e32 v1, v74, v74
	v_fmac_f32_e32 v104, v76, v76
	v_add_f32_e32 v1, v1, v104
	ds_bpermute_b32 v104, v35, v1
	s_waitcnt lgkmcnt(0)
	v_add_f32_e32 v104, v1, v104
	ds_bpermute_b32 v105, v90, v104
	s_and_saveexec_b64 s[20:21], s[36:37]
	s_nop 0
	s_waitcnt lgkmcnt(0)
	v_add_f32_e32 v1, v104, v105
	v_add_u32_e32 v104, s95, v143
	ds_write_b32 v104, v1
	s_or_b64 exec, exec, s[20:21]
	s_nop 0
	s_nop 0
	v_cmp_gt_i32_e64 s[64:65], s5, v96
	v_mov_b32_e32 v110, 0
	v_lshl_add_u64 v[108:109], s[18:19], 0, v[96:97]
	v_mov_b32_e32 v111, 0
	s_nop 0
	v_mfma_f32_16x16x32_bf16 v[70:73], v[62:65], v[200:203], v[70:73]
	s_nop 0
	s_nop 0
	v_mfma_f32_16x16x32_bf16 v[70:73], v[58:61], v[204:207], v[70:73]
	s_and_saveexec_b64 s[20:21], s[64:65]
	s_nop 0
	v_lshlrev_b64 v[104:105], 12, v[108:109]
	v_lshl_add_u64 v[104:105], v[102:103], 0, v[104:105]
	global_load_dwordx2 v[110:111], v[104:105], off
	s_or_b64 exec, exec, s[20:21]
	s_nop 4
	v_mul_f32_e32 v1, v71, v71
	v_mul_f32_e32 v104, v73, v73
	v_fmac_f32_e32 v1, v70, v70
	v_fmac_f32_e32 v104, v72, v72
	v_add_f32_e32 v1, v1, v104
	ds_bpermute_b32 v104, v35, v1
	s_waitcnt lgkmcnt(0)
	v_add_f32_e32 v104, v1, v104
	ds_bpermute_b32 v105, v90, v104
	s_and_saveexec_b64 s[20:21], s[36:37]
	s_nop 0
	s_waitcnt lgkmcnt(0)
	v_add_f32_e32 v1, v104, v105
	v_add_u32_e32 v104, s95, v145
	ds_write_b32 v104, v1
	s_or_b64 exec, exec, s[20:21]
	s_nop 0
	s_nop 0
	v_cmp_gt_i32_e64 s[62:63], s5, v98
	s_nop 0
	v_mfma_f32_16x16x32_bf16 v[66:69], v[62:65], v[184:187], v[66:69]
	s_nop 0
	s_nop 0
	v_mfma_f32_16x16x32_bf16 v[66:69], v[58:61], v[188:191], v[66:69]
	v_mov_b32_e32 v106, 0
	v_lshl_add_u64 v[104:105], s[18:19], 0, v[98:99]
	v_mov_b32_e32 v107, 0
	s_and_saveexec_b64 s[20:21], s[62:63]
	s_nop 0
	v_lshlrev_b64 v[106:107], 12, v[104:105]
	v_lshl_add_u64 v[106:107], v[102:103], 0, v[106:107]
	global_load_dwordx2 v[106:107], v[106:107], off
	s_or_b64 exec, exec, s[20:21]
	s_nop 1
	v_mul_f32_e32 v1, v67, v67
	v_mul_f32_e32 v113, v69, v69
	v_fmac_f32_e32 v1, v66, v66
	v_fmac_f32_e32 v113, v68, v68
	v_add_f32_e32 v1, v1, v113
	ds_bpermute_b32 v35, v35, v1
	s_waitcnt lgkmcnt(0)
	v_add_f32_e32 v35, v1, v35
	ds_bpermute_b32 v90, v90, v35
	s_and_saveexec_b64 s[20:21], s[36:37]
	s_nop 0
	s_waitcnt lgkmcnt(0)
	v_add_f32_e32 v1, v35, v90
	v_add_u32_e32 v35, s95, v146
	ds_write_b32 v35, v1
	s_or_b64 exec, exec, s[20:21]
